# v40 = v37 (all A loads early) + w_in epilogue deferred under the next tile's prologue loads
# speedup vs baseline: 1.0015x; 1.0015x over previous
.Lv5_c_0:
	ds_write_b128 v189, v[164:167]
	ds_write_b128 v189, v[128:131] offset:4608
	ds_write_b128 v189, v[132:135] offset:9216
	ds_write_b128 v189, v[136:139] offset:13824
	ds_write_b128 v189, v[144:147] offset:18432
	ds_write_b128 v189, v[148:151] offset:23040
	ds_write_b128 v189, v[152:155] offset:27648
	ds_write_b128 v189, v[156:159] offset:32256
	ds_write_b128 v189, v[140:143] offset:36864
	ds_write_b128 v189, v[160:163] offset:41472
	ds_write_b128 v189, v[168:171] offset:46080
	ds_write_b128 v189, v[172:175] offset:50688
	global_load_dwordx4 v[164:167], v190, s[40:41]
	global_load_dwordx4 v[128:131], v191, s[40:41]
	global_load_dwordx4 v[132:135], v192, s[40:41]
	global_load_dwordx4 v[136:139], v193, s[40:41]
	global_load_dwordx4 v[144:147], v194, s[40:41]
	global_load_dwordx4 v[148:151], v195, s[40:41]
	global_load_dwordx4 v[152:155], v196, s[40:41]
	global_load_dwordx4 v[156:159], v197, s[40:41]
	s_waitcnt lgkmcnt(0)
	s_barrier
.LBB0_302:
	ds_read_b128 v[216:219], v176 offset:36864
	ds_read_b128 v[200:203], v188
	ds_read_b128 v[220:223], v176 offset:41472
	ds_read_b128 v[204:207], v188 offset:4608
	ds_read_b128 v[208:211], v188 offset:9216
	ds_read_b128 v[212:215], v187
	s_waitcnt lgkmcnt(4)
	v_mfma_f32_32x32x16_bf16 v[112:127], v[200:203], v[216:219], v[112:127]
	ds_read_b128 v[240:243], v176 offset:36896
	global_load_dwordx4 v[140:143], v190, s[42:43]
	s_waitcnt lgkmcnt(4)
	v_mfma_f32_32x32x16_bf16 v[96:111], v[200:203], v[220:223], v[96:111]
	ds_read_b128 v[224:227], v188 offset:32
	global_load_dwordx4 v[160:163], v191, s[42:43]
	s_waitcnt lgkmcnt(4)
	v_mfma_f32_32x32x16_bf16 v[80:95], v[204:207], v[216:219], v[80:95]
	ds_read_b128 v[244:247], v176 offset:41504
	global_load_dwordx4 v[168:171], v192, s[42:43]
	s_waitcnt lgkmcnt(5)
	v_mfma_f32_32x32x16_bf16 v[64:79], v[204:207], v[220:223], v[64:79]
	ds_read_b128 v[228:231], v188 offset:4640
	global_load_dwordx4 v[172:175], v193, s[42:43]
	s_add_u32 s40, s40, 0x80
	s_addc_u32 s41, s41, 0
	s_add_u32 s42, s42, 0x80
	s_addc_u32 s43, s43, 0
	s_add_u32 s16, s16, 0x80
	s_waitcnt lgkmcnt(5)
	v_mfma_f32_32x32x16_bf16 v[48:63], v[208:211], v[216:219], v[48:63]
	ds_read_b128 v[232:235], v188 offset:9248
	s_waitcnt lgkmcnt(6)
	v_mfma_f32_32x32x16_bf16 v[32:47], v[208:211], v[220:223], v[32:47]
	ds_read_b128 v[236:239], v187 offset:32
	s_waitcnt lgkmcnt(6)
	v_mfma_f32_32x32x16_bf16 v[16:31], v[212:215], v[216:219], v[16:31]
	s_waitcnt lgkmcnt(6)
	v_mfma_f32_32x32x16_bf16 v[0:15], v[212:215], v[220:223], v[0:15]
	s_waitcnt lgkmcnt(4)
	v_mfma_f32_32x32x16_bf16 v[112:127], v[224:227], v[240:243], v[112:127]
	ds_read_b128 v[200:203], v188 offset:64
	s_waitcnt lgkmcnt(4)
	v_mfma_f32_32x32x16_bf16 v[96:111], v[224:227], v[244:247], v[96:111]
	ds_read_b128 v[204:207], v188 offset:4672
	s_waitcnt lgkmcnt(4)
	v_mfma_f32_32x32x16_bf16 v[80:95], v[228:231], v[240:243], v[80:95]
	ds_read_b128 v[208:211], v188 offset:9280
	s_waitcnt lgkmcnt(5)
	v_mfma_f32_32x32x16_bf16 v[64:79], v[228:231], v[244:247], v[64:79]
	ds_read_b128 v[212:215], v187 offset:64
	s_waitcnt lgkmcnt(5)
	v_mfma_f32_32x32x16_bf16 v[48:63], v[232:235], v[240:243], v[48:63]
	ds_read_b128 v[216:219], v176 offset:36928
	s_waitcnt lgkmcnt(6)
	v_mfma_f32_32x32x16_bf16 v[32:47], v[232:235], v[244:247], v[32:47]
	ds_read_b128 v[220:223], v176 offset:41536
	s_waitcnt lgkmcnt(6)
	v_mfma_f32_32x32x16_bf16 v[16:31], v[236:239], v[240:243], v[16:31]
	s_waitcnt lgkmcnt(6)
	v_mfma_f32_32x32x16_bf16 v[0:15], v[236:239], v[244:247], v[0:15]
	s_waitcnt lgkmcnt(1)
	v_mfma_f32_32x32x16_bf16 v[112:127], v[200:203], v[216:219], v[112:127]
	ds_read_b128 v[224:227], v188 offset:96
	s_waitcnt lgkmcnt(1)
	v_mfma_f32_32x32x16_bf16 v[96:111], v[200:203], v[220:223], v[96:111]
	ds_read_b128 v[228:231], v188 offset:4704
	s_waitcnt lgkmcnt(3)
	v_mfma_f32_32x32x16_bf16 v[80:95], v[204:207], v[216:219], v[80:95]
	ds_read_b128 v[232:235], v188 offset:9312
	s_waitcnt lgkmcnt(3)
	v_mfma_f32_32x32x16_bf16 v[64:79], v[204:207], v[220:223], v[64:79]
	ds_read_b128 v[236:239], v187 offset:96
	s_waitcnt lgkmcnt(5)
	v_mfma_f32_32x32x16_bf16 v[48:63], v[208:211], v[216:219], v[48:63]
	ds_read_b128 v[240:243], v176 offset:36960
	s_waitcnt lgkmcnt(5)
	v_mfma_f32_32x32x16_bf16 v[32:47], v[208:211], v[220:223], v[32:47]
	ds_read_b128 v[244:247], v176 offset:41568
	s_waitcnt lgkmcnt(7)
	v_mfma_f32_32x32x16_bf16 v[16:31], v[212:215], v[216:219], v[16:31]
	s_waitcnt lgkmcnt(6)
	v_mfma_f32_32x32x16_bf16 v[0:15], v[212:215], v[220:223], v[0:15]
	s_waitcnt lgkmcnt(0)
	s_barrier
	s_waitcnt vmcnt(4)
	s_waitcnt lgkmcnt(1)
	v_mfma_f32_32x32x16_bf16 v[112:127], v[224:227], v[240:243], v[112:127]
	ds_write_b128 v189, v[164:167]
	ds_write_b128 v189, v[128:131] offset:4608
	s_waitcnt lgkmcnt(2)
	v_mfma_f32_32x32x16_bf16 v[96:111], v[224:227], v[244:247], v[96:111]
	ds_write_b128 v189, v[132:135] offset:9216
	global_load_dwordx4 v[164:167], v190, s[40:41]
	s_waitcnt lgkmcnt(4)
	v_mfma_f32_32x32x16_bf16 v[80:95], v[228:231], v[240:243], v[80:95]
	ds_write_b128 v189, v[136:139] offset:13824
	ds_write_b128 v189, v[144:147] offset:18432
	global_load_dwordx4 v[128:131], v191, s[40:41]
	s_waitcnt lgkmcnt(5)
	v_mfma_f32_32x32x16_bf16 v[64:79], v[228:231], v[244:247], v[64:79]
	ds_write_b128 v189, v[148:151] offset:23040
	global_load_dwordx4 v[132:135], v192, s[40:41]
	s_waitcnt lgkmcnt(7)
	v_mfma_f32_32x32x16_bf16 v[48:63], v[232:235], v[240:243], v[48:63]
	ds_write_b128 v189, v[152:155] offset:27648
	ds_write_b128 v189, v[156:159] offset:32256
	global_load_dwordx4 v[136:139], v193, s[40:41]
	s_waitcnt lgkmcnt(8)
	v_mfma_f32_32x32x16_bf16 v[32:47], v[232:235], v[244:247], v[32:47]
	s_waitcnt vmcnt(4)
	ds_write_b128 v189, v[140:143] offset:36864
	global_load_dwordx4 v[144:147], v194, s[40:41]
	s_waitcnt lgkmcnt(10)
	v_mfma_f32_32x32x16_bf16 v[16:31], v[236:239], v[240:243], v[16:31]
	ds_write_b128 v189, v[160:163] offset:41472
	ds_write_b128 v189, v[168:171] offset:46080
	global_load_dwordx4 v[148:151], v195, s[40:41]
	s_waitcnt lgkmcnt(11)
	v_mfma_f32_32x32x16_bf16 v[0:15], v[236:239], v[244:247], v[0:15]
	ds_write_b128 v189, v[172:175] offset:50688
	global_load_dwordx4 v[152:155], v196, s[40:41]
	global_load_dwordx4 v[156:159], v197, s[40:41]
	s_waitcnt lgkmcnt(0)
	s_barrier
	s_cmpk_lg_i32 s16, 0x780
	s_cbranch_scc1 .LBB0_302
	ds_read_b128 v[216:219], v176 offset:36864
	ds_read_b128 v[200:203], v188
	ds_read_b128 v[220:223], v176 offset:41472
	ds_read_b128 v[204:207], v188 offset:4608
	ds_read_b128 v[208:211], v188 offset:9216
	ds_read_b128 v[212:215], v187
	s_waitcnt lgkmcnt(4)
	v_mfma_f32_32x32x16_bf16 v[112:127], v[200:203], v[216:219], v[112:127]
	ds_read_b128 v[240:243], v176 offset:36896
	s_waitcnt lgkmcnt(4)
	v_mfma_f32_32x32x16_bf16 v[96:111], v[200:203], v[220:223], v[96:111]
	ds_read_b128 v[224:227], v188 offset:32
	s_waitcnt lgkmcnt(4)
	v_mfma_f32_32x32x16_bf16 v[80:95], v[204:207], v[216:219], v[80:95]
	ds_read_b128 v[244:247], v176 offset:41504
	s_waitcnt lgkmcnt(5)
	v_mfma_f32_32x32x16_bf16 v[64:79], v[204:207], v[220:223], v[64:79]
	ds_read_b128 v[228:231], v188 offset:4640
	s_waitcnt lgkmcnt(5)
	v_mfma_f32_32x32x16_bf16 v[48:63], v[208:211], v[216:219], v[48:63]
	ds_read_b128 v[232:235], v188 offset:9248
	s_waitcnt lgkmcnt(6)
	v_mfma_f32_32x32x16_bf16 v[32:47], v[208:211], v[220:223], v[32:47]
	ds_read_b128 v[236:239], v187 offset:32
	s_waitcnt lgkmcnt(6)
	v_mfma_f32_32x32x16_bf16 v[16:31], v[212:215], v[216:219], v[16:31]
	s_waitcnt lgkmcnt(6)
	v_mfma_f32_32x32x16_bf16 v[0:15], v[212:215], v[220:223], v[0:15]
	s_waitcnt lgkmcnt(4)
	v_mfma_f32_32x32x16_bf16 v[112:127], v[224:227], v[240:243], v[112:127]
	ds_read_b128 v[200:203], v188 offset:64
	s_waitcnt lgkmcnt(4)
	v_mfma_f32_32x32x16_bf16 v[96:111], v[224:227], v[244:247], v[96:111]
	ds_read_b128 v[204:207], v188 offset:4672
	s_waitcnt lgkmcnt(4)
	v_mfma_f32_32x32x16_bf16 v[80:95], v[228:231], v[240:243], v[80:95]
	ds_read_b128 v[208:211], v188 offset:9280
	s_waitcnt lgkmcnt(5)
	v_mfma_f32_32x32x16_bf16 v[64:79], v[228:231], v[244:247], v[64:79]
	ds_read_b128 v[212:215], v187 offset:64
	s_waitcnt lgkmcnt(5)
	v_mfma_f32_32x32x16_bf16 v[48:63], v[232:235], v[240:243], v[48:63]
	ds_read_b128 v[216:219], v176 offset:36928
	s_waitcnt lgkmcnt(6)
	v_mfma_f32_32x32x16_bf16 v[32:47], v[232:235], v[244:247], v[32:47]
	ds_read_b128 v[220:223], v176 offset:41536
	s_waitcnt lgkmcnt(6)
	v_mfma_f32_32x32x16_bf16 v[16:31], v[236:239], v[240:243], v[16:31]
	s_waitcnt lgkmcnt(6)
	v_mfma_f32_32x32x16_bf16 v[0:15], v[236:239], v[244:247], v[0:15]
	s_waitcnt lgkmcnt(1)
	v_mfma_f32_32x32x16_bf16 v[112:127], v[200:203], v[216:219], v[112:127]
	ds_read_b128 v[224:227], v188 offset:96
	s_waitcnt lgkmcnt(1)
	v_mfma_f32_32x32x16_bf16 v[96:111], v[200:203], v[220:223], v[96:111]
	ds_read_b128 v[228:231], v188 offset:4704
	s_waitcnt lgkmcnt(3)
	v_mfma_f32_32x32x16_bf16 v[80:95], v[204:207], v[216:219], v[80:95]
	ds_read_b128 v[232:235], v188 offset:9312
	s_waitcnt lgkmcnt(3)
	v_mfma_f32_32x32x16_bf16 v[64:79], v[204:207], v[220:223], v[64:79]
	ds_read_b128 v[236:239], v187 offset:96
	s_waitcnt lgkmcnt(5)
	v_mfma_f32_32x32x16_bf16 v[48:63], v[208:211], v[216:219], v[48:63]
	ds_read_b128 v[240:243], v176 offset:36960
	s_waitcnt lgkmcnt(5)
	v_mfma_f32_32x32x16_bf16 v[32:47], v[208:211], v[220:223], v[32:47]
	ds_read_b128 v[244:247], v176 offset:41568
	s_waitcnt lgkmcnt(7)
	v_mfma_f32_32x32x16_bf16 v[16:31], v[212:215], v[216:219], v[16:31]
	s_waitcnt lgkmcnt(6)
	v_mfma_f32_32x32x16_bf16 v[0:15], v[212:215], v[220:223], v[0:15]
	s_waitcnt lgkmcnt(1)
	v_mfma_f32_32x32x16_bf16 v[112:127], v[224:227], v[240:243], v[112:127]
	s_waitcnt lgkmcnt(0)
	v_mfma_f32_32x32x16_bf16 v[96:111], v[224:227], v[244:247], v[96:111]
	s_waitcnt lgkmcnt(1)
	v_mfma_f32_32x32x16_bf16 v[80:95], v[228:231], v[240:243], v[80:95]
	s_waitcnt lgkmcnt(0)
	v_mfma_f32_32x32x16_bf16 v[64:79], v[228:231], v[244:247], v[64:79]
	s_waitcnt lgkmcnt(1)
	v_mfma_f32_32x32x16_bf16 v[48:63], v[232:235], v[240:243], v[48:63]
	s_waitcnt lgkmcnt(0)
	v_mfma_f32_32x32x16_bf16 v[32:47], v[232:235], v[244:247], v[32:47]
	s_waitcnt lgkmcnt(1)
	v_mfma_f32_32x32x16_bf16 v[16:31], v[236:239], v[240:243], v[16:31]
	s_waitcnt lgkmcnt(0)
	v_mfma_f32_32x32x16_bf16 v[0:15], v[236:239], v[244:247], v[0:15]
	s_waitcnt vmcnt(0)
	s_mul_i32 s44, s12, 0x1240
	s_add_u32 s46, s30, s44
	s_addc_u32 s47, s31, 0
	s_lshl_b32 s44, s8, 1
	s_add_u32 s46, s46, s44
	s_addc_u32 s47, s47, 0
	s_add_u32 s46, s46, 0x7157900
	s_addc_u32 s47, s47, 0
	s_cmp_eq_u32 s8, 0x900
	s_cselect_b32 s45, 2, 1
	v_cvt_pk_bf16_f32 v190, v112, v113
	v_cvt_pk_bf16_f32 v191, v114, v115
	v_cvt_pk_bf16_f32 v192, v116, v117
	v_cvt_pk_bf16_f32 v193, v118, v119
	v_cvt_pk_bf16_f32 v194, v120, v121
	v_cvt_pk_bf16_f32 v195, v122, v123
	v_cvt_pk_bf16_f32 v196, v124, v125
	v_cvt_pk_bf16_f32 v197, v126, v127
	v_cvt_pk_bf16_f32 v198, v96, v97
	v_cvt_pk_bf16_f32 v199, v98, v99
	v_cvt_pk_bf16_f32 v200, v100, v101
	v_cvt_pk_bf16_f32 v201, v102, v103
	v_cvt_pk_bf16_f32 v202, v104, v105
	v_cvt_pk_bf16_f32 v203, v106, v107
	v_cvt_pk_bf16_f32 v204, v108, v109
	v_cvt_pk_bf16_f32 v205, v110, v111
	v_cvt_pk_bf16_f32 v206, v80, v81
	v_cvt_pk_bf16_f32 v207, v82, v83
	v_cvt_pk_bf16_f32 v208, v84, v85
	v_cvt_pk_bf16_f32 v209, v86, v87
	v_cvt_pk_bf16_f32 v210, v88, v89
	v_cvt_pk_bf16_f32 v211, v90, v91
	v_cvt_pk_bf16_f32 v212, v92, v93
	v_cvt_pk_bf16_f32 v213, v94, v95
	v_cvt_pk_bf16_f32 v214, v64, v65
	v_cvt_pk_bf16_f32 v215, v66, v67
	v_cvt_pk_bf16_f32 v216, v68, v69
	v_cvt_pk_bf16_f32 v217, v70, v71
	v_cvt_pk_bf16_f32 v218, v72, v73
	v_cvt_pk_bf16_f32 v219, v74, v75
	v_cvt_pk_bf16_f32 v220, v76, v77
	v_cvt_pk_bf16_f32 v221, v78, v79
	v_cvt_pk_bf16_f32 v222, v48, v49
	v_cvt_pk_bf16_f32 v223, v50, v51
	v_cvt_pk_bf16_f32 v224, v52, v53
	v_cvt_pk_bf16_f32 v225, v54, v55
	v_cvt_pk_bf16_f32 v226, v56, v57
	v_cvt_pk_bf16_f32 v227, v58, v59
	v_cvt_pk_bf16_f32 v228, v60, v61
	v_cvt_pk_bf16_f32 v229, v62, v63
	v_cvt_pk_bf16_f32 v230, v32, v33
	v_cvt_pk_bf16_f32 v231, v34, v35
	v_cvt_pk_bf16_f32 v232, v36, v37
	v_cvt_pk_bf16_f32 v233, v38, v39
	v_cvt_pk_bf16_f32 v234, v40, v41
	v_cvt_pk_bf16_f32 v235, v42, v43
	v_cvt_pk_bf16_f32 v236, v44, v45
	v_cvt_pk_bf16_f32 v237, v46, v47
	v_cvt_pk_bf16_f32 v238, v16, v17
	v_cvt_pk_bf16_f32 v239, v18, v19
	v_cvt_pk_bf16_f32 v240, v20, v21
	v_cvt_pk_bf16_f32 v241, v22, v23
	v_cvt_pk_bf16_f32 v242, v24, v25
	v_cvt_pk_bf16_f32 v243, v26, v27
	v_cvt_pk_bf16_f32 v244, v28, v29
	v_cvt_pk_bf16_f32 v245, v30, v31
	v_cvt_pk_bf16_f32 v246, v0, v1
	v_cvt_pk_bf16_f32 v247, v2, v3
	v_cvt_pk_bf16_f32 v248, v4, v5
	v_cvt_pk_bf16_f32 v249, v6, v7
	v_cvt_pk_bf16_f32 v250, v8, v9
	v_cvt_pk_bf16_f32 v251, v10, v11
	v_cvt_pk_bf16_f32 v252, v12, v13
	v_cvt_pk_bf16_f32 v253, v14, v15
	s_branch .Lmt4_tail_0

.Lv5_c_2:
	ds_write_b128 v189, v[164:167]
	ds_write_b128 v189, v[128:131] offset:4608
	ds_write_b128 v189, v[132:135] offset:9216
	ds_write_b128 v189, v[136:139] offset:13824
	ds_write_b128 v189, v[144:147] offset:18432
	ds_write_b128 v189, v[148:151] offset:23040
	ds_write_b128 v189, v[152:155] offset:27648
	ds_write_b128 v189, v[156:159] offset:32256
	ds_write_b128 v189, v[140:143] offset:36864
	ds_write_b128 v189, v[160:163] offset:41472
	ds_write_b128 v189, v[168:171] offset:46080
	ds_write_b128 v189, v[172:175] offset:50688
	global_load_dwordx4 v[164:167], v190, s[42:43]
	global_load_dwordx4 v[128:131], v191, s[42:43]
	global_load_dwordx4 v[132:135], v192, s[42:43]
	global_load_dwordx4 v[136:139], v193, s[42:43]
	global_load_dwordx4 v[144:147], v194, s[42:43]
	global_load_dwordx4 v[148:151], v195, s[42:43]
	global_load_dwordx4 v[152:155], v196, s[42:43]
	global_load_dwordx4 v[156:159], v197, s[42:43]
	s_waitcnt lgkmcnt(0)
	s_barrier
.LBB0_1284:
	ds_read_b128 v[216:219], v176 offset:36864
	ds_read_b128 v[200:203], v188
	ds_read_b128 v[220:223], v176 offset:41472
	ds_read_b128 v[204:207], v188 offset:4608
	ds_read_b128 v[208:211], v188 offset:9216
	ds_read_b128 v[212:215], v187
	s_waitcnt lgkmcnt(4)
	v_mfma_f32_32x32x16_bf16 v[112:127], v[200:203], v[216:219], v[112:127]
	ds_read_b128 v[240:243], v176 offset:36896
	global_load_dwordx4 v[140:143], v190, s[44:45]
	s_waitcnt lgkmcnt(4)
	v_mfma_f32_32x32x16_bf16 v[96:111], v[200:203], v[220:223], v[96:111]
	ds_read_b128 v[224:227], v188 offset:32
	global_load_dwordx4 v[160:163], v191, s[44:45]
	s_waitcnt lgkmcnt(4)
	v_mfma_f32_32x32x16_bf16 v[80:95], v[204:207], v[216:219], v[80:95]
	ds_read_b128 v[244:247], v176 offset:41504
	global_load_dwordx4 v[168:171], v192, s[44:45]
	s_waitcnt lgkmcnt(5)
	v_mfma_f32_32x32x16_bf16 v[64:79], v[204:207], v[220:223], v[64:79]
	ds_read_b128 v[228:231], v188 offset:4640
	global_load_dwordx4 v[172:175], v193, s[44:45]
	s_add_u32 s42, s42, 0x80
	s_addc_u32 s43, s43, 0
	s_add_u32 s44, s44, 0x80
	s_addc_u32 s45, s45, 0
	s_add_u32 s16, s16, 0x80
	s_waitcnt lgkmcnt(5)
	v_mfma_f32_32x32x16_bf16 v[48:63], v[208:211], v[216:219], v[48:63]
	ds_read_b128 v[232:235], v188 offset:9248
	s_waitcnt lgkmcnt(6)
	v_mfma_f32_32x32x16_bf16 v[32:47], v[208:211], v[220:223], v[32:47]
	ds_read_b128 v[236:239], v187 offset:32
	s_waitcnt lgkmcnt(6)
	v_mfma_f32_32x32x16_bf16 v[16:31], v[212:215], v[216:219], v[16:31]
	s_waitcnt lgkmcnt(6)
	v_mfma_f32_32x32x16_bf16 v[0:15], v[212:215], v[220:223], v[0:15]
	s_waitcnt lgkmcnt(4)
	v_mfma_f32_32x32x16_bf16 v[112:127], v[224:227], v[240:243], v[112:127]
	ds_read_b128 v[200:203], v188 offset:64
	s_waitcnt lgkmcnt(4)
	v_mfma_f32_32x32x16_bf16 v[96:111], v[224:227], v[244:247], v[96:111]
	ds_read_b128 v[204:207], v188 offset:4672
	s_waitcnt lgkmcnt(4)
	v_mfma_f32_32x32x16_bf16 v[80:95], v[228:231], v[240:243], v[80:95]
	ds_read_b128 v[208:211], v188 offset:9280
	s_waitcnt lgkmcnt(5)
	v_mfma_f32_32x32x16_bf16 v[64:79], v[228:231], v[244:247], v[64:79]
	ds_read_b128 v[212:215], v187 offset:64
	s_waitcnt lgkmcnt(5)
	v_mfma_f32_32x32x16_bf16 v[48:63], v[232:235], v[240:243], v[48:63]
	ds_read_b128 v[216:219], v176 offset:36928
	s_waitcnt lgkmcnt(6)
	v_mfma_f32_32x32x16_bf16 v[32:47], v[232:235], v[244:247], v[32:47]
	ds_read_b128 v[220:223], v176 offset:41536
	s_waitcnt lgkmcnt(6)
	v_mfma_f32_32x32x16_bf16 v[16:31], v[236:239], v[240:243], v[16:31]
	s_waitcnt lgkmcnt(6)
	v_mfma_f32_32x32x16_bf16 v[0:15], v[236:239], v[244:247], v[0:15]
	s_waitcnt lgkmcnt(1)
	v_mfma_f32_32x32x16_bf16 v[112:127], v[200:203], v[216:219], v[112:127]
	ds_read_b128 v[224:227], v188 offset:96
	s_waitcnt lgkmcnt(1)
	v_mfma_f32_32x32x16_bf16 v[96:111], v[200:203], v[220:223], v[96:111]
	ds_read_b128 v[228:231], v188 offset:4704
	s_waitcnt lgkmcnt(3)
	v_mfma_f32_32x32x16_bf16 v[80:95], v[204:207], v[216:219], v[80:95]
	ds_read_b128 v[232:235], v188 offset:9312
	s_waitcnt lgkmcnt(3)
	v_mfma_f32_32x32x16_bf16 v[64:79], v[204:207], v[220:223], v[64:79]
	ds_read_b128 v[236:239], v187 offset:96
	s_waitcnt lgkmcnt(5)
	v_mfma_f32_32x32x16_bf16 v[48:63], v[208:211], v[216:219], v[48:63]
	ds_read_b128 v[240:243], v176 offset:36960
	s_waitcnt lgkmcnt(5)
	v_mfma_f32_32x32x16_bf16 v[32:47], v[208:211], v[220:223], v[32:47]
	ds_read_b128 v[244:247], v176 offset:41568
	s_waitcnt lgkmcnt(7)
	v_mfma_f32_32x32x16_bf16 v[16:31], v[212:215], v[216:219], v[16:31]
	s_waitcnt lgkmcnt(6)
	v_mfma_f32_32x32x16_bf16 v[0:15], v[212:215], v[220:223], v[0:15]
	s_waitcnt lgkmcnt(0)
	s_barrier
	s_waitcnt vmcnt(4)
	s_waitcnt lgkmcnt(1)
	v_mfma_f32_32x32x16_bf16 v[112:127], v[224:227], v[240:243], v[112:127]
	ds_write_b128 v189, v[164:167]
	ds_write_b128 v189, v[128:131] offset:4608
	s_waitcnt lgkmcnt(2)
	v_mfma_f32_32x32x16_bf16 v[96:111], v[224:227], v[244:247], v[96:111]
	ds_write_b128 v189, v[132:135] offset:9216
	global_load_dwordx4 v[164:167], v190, s[42:43]
	s_waitcnt lgkmcnt(4)
	v_mfma_f32_32x32x16_bf16 v[80:95], v[228:231], v[240:243], v[80:95]
	ds_write_b128 v189, v[136:139] offset:13824
	ds_write_b128 v189, v[144:147] offset:18432
	global_load_dwordx4 v[128:131], v191, s[42:43]
	s_waitcnt lgkmcnt(5)
	v_mfma_f32_32x32x16_bf16 v[64:79], v[228:231], v[244:247], v[64:79]
	ds_write_b128 v189, v[148:151] offset:23040
	global_load_dwordx4 v[132:135], v192, s[42:43]
	s_waitcnt lgkmcnt(7)
	v_mfma_f32_32x32x16_bf16 v[48:63], v[232:235], v[240:243], v[48:63]
	ds_write_b128 v189, v[152:155] offset:27648
	ds_write_b128 v189, v[156:159] offset:32256
	global_load_dwordx4 v[136:139], v193, s[42:43]
	s_waitcnt lgkmcnt(8)
	v_mfma_f32_32x32x16_bf16 v[32:47], v[232:235], v[244:247], v[32:47]
	s_waitcnt vmcnt(4)
	ds_write_b128 v189, v[140:143] offset:36864
	global_load_dwordx4 v[144:147], v194, s[42:43]
	s_waitcnt lgkmcnt(10)
	v_mfma_f32_32x32x16_bf16 v[16:31], v[236:239], v[240:243], v[16:31]
	ds_write_b128 v189, v[160:163] offset:41472
	ds_write_b128 v189, v[168:171] offset:46080
	global_load_dwordx4 v[148:151], v195, s[42:43]
	s_waitcnt lgkmcnt(11)
	v_mfma_f32_32x32x16_bf16 v[0:15], v[236:239], v[244:247], v[0:15]
	ds_write_b128 v189, v[172:175] offset:50688
	global_load_dwordx4 v[152:155], v196, s[42:43]
	global_load_dwordx4 v[156:159], v197, s[42:43]
	s_waitcnt lgkmcnt(0)
	s_barrier
	s_cmpk_lg_i32 s16, 0x780
	s_cbranch_scc1 .LBB0_1284
	ds_read_b128 v[216:219], v176 offset:36864
	ds_read_b128 v[200:203], v188
	ds_read_b128 v[220:223], v176 offset:41472
	ds_read_b128 v[204:207], v188 offset:4608
	ds_read_b128 v[208:211], v188 offset:9216
	ds_read_b128 v[212:215], v187
	s_waitcnt lgkmcnt(4)
	v_mfma_f32_32x32x16_bf16 v[112:127], v[200:203], v[216:219], v[112:127]
	ds_read_b128 v[240:243], v176 offset:36896
	s_waitcnt lgkmcnt(4)
	v_mfma_f32_32x32x16_bf16 v[96:111], v[200:203], v[220:223], v[96:111]
	ds_read_b128 v[224:227], v188 offset:32
	s_waitcnt lgkmcnt(4)
	v_mfma_f32_32x32x16_bf16 v[80:95], v[204:207], v[216:219], v[80:95]
	ds_read_b128 v[244:247], v176 offset:41504
	s_waitcnt lgkmcnt(5)
	v_mfma_f32_32x32x16_bf16 v[64:79], v[204:207], v[220:223], v[64:79]
	ds_read_b128 v[228:231], v188 offset:4640
	s_waitcnt lgkmcnt(5)
	v_mfma_f32_32x32x16_bf16 v[48:63], v[208:211], v[216:219], v[48:63]
	ds_read_b128 v[232:235], v188 offset:9248
	s_waitcnt lgkmcnt(6)
	v_mfma_f32_32x32x16_bf16 v[32:47], v[208:211], v[220:223], v[32:47]
	ds_read_b128 v[236:239], v187 offset:32
	s_waitcnt lgkmcnt(6)
	v_mfma_f32_32x32x16_bf16 v[16:31], v[212:215], v[216:219], v[16:31]
	s_waitcnt lgkmcnt(6)
	v_mfma_f32_32x32x16_bf16 v[0:15], v[212:215], v[220:223], v[0:15]
	s_waitcnt lgkmcnt(4)
	v_mfma_f32_32x32x16_bf16 v[112:127], v[224:227], v[240:243], v[112:127]
	ds_read_b128 v[200:203], v188 offset:64
	s_waitcnt lgkmcnt(4)
	v_mfma_f32_32x32x16_bf16 v[96:111], v[224:227], v[244:247], v[96:111]
	ds_read_b128 v[204:207], v188 offset:4672
	s_waitcnt lgkmcnt(4)
	v_mfma_f32_32x32x16_bf16 v[80:95], v[228:231], v[240:243], v[80:95]
	ds_read_b128 v[208:211], v188 offset:9280
	s_waitcnt lgkmcnt(5)
	v_mfma_f32_32x32x16_bf16 v[64:79], v[228:231], v[244:247], v[64:79]
	ds_read_b128 v[212:215], v187 offset:64
	s_waitcnt lgkmcnt(5)
	v_mfma_f32_32x32x16_bf16 v[48:63], v[232:235], v[240:243], v[48:63]
	ds_read_b128 v[216:219], v176 offset:36928
	s_waitcnt lgkmcnt(6)
	v_mfma_f32_32x32x16_bf16 v[32:47], v[232:235], v[244:247], v[32:47]
	ds_read_b128 v[220:223], v176 offset:41536
	s_waitcnt lgkmcnt(6)
	v_mfma_f32_32x32x16_bf16 v[16:31], v[236:239], v[240:243], v[16:31]
	s_waitcnt lgkmcnt(6)
	v_mfma_f32_32x32x16_bf16 v[0:15], v[236:239], v[244:247], v[0:15]
	s_waitcnt lgkmcnt(1)
	v_mfma_f32_32x32x16_bf16 v[112:127], v[200:203], v[216:219], v[112:127]
	ds_read_b128 v[224:227], v188 offset:96
	s_waitcnt lgkmcnt(1)
	v_mfma_f32_32x32x16_bf16 v[96:111], v[200:203], v[220:223], v[96:111]
	ds_read_b128 v[228:231], v188 offset:4704
	s_waitcnt lgkmcnt(3)
	v_mfma_f32_32x32x16_bf16 v[80:95], v[204:207], v[216:219], v[80:95]
	ds_read_b128 v[232:235], v188 offset:9312
	s_waitcnt lgkmcnt(3)
	v_mfma_f32_32x32x16_bf16 v[64:79], v[204:207], v[220:223], v[64:79]
	ds_read_b128 v[236:239], v187 offset:96
	s_waitcnt lgkmcnt(5)
	v_mfma_f32_32x32x16_bf16 v[48:63], v[208:211], v[216:219], v[48:63]
	ds_read_b128 v[240:243], v176 offset:36960
	s_waitcnt lgkmcnt(5)
	v_mfma_f32_32x32x16_bf16 v[32:47], v[208:211], v[220:223], v[32:47]
	ds_read_b128 v[244:247], v176 offset:41568
	s_waitcnt lgkmcnt(7)
	v_mfma_f32_32x32x16_bf16 v[16:31], v[212:215], v[216:219], v[16:31]
	s_waitcnt lgkmcnt(6)
	v_mfma_f32_32x32x16_bf16 v[0:15], v[212:215], v[220:223], v[0:15]
	s_waitcnt lgkmcnt(1)
	v_mfma_f32_32x32x16_bf16 v[112:127], v[224:227], v[240:243], v[112:127]
	s_waitcnt lgkmcnt(0)
	v_mfma_f32_32x32x16_bf16 v[96:111], v[224:227], v[244:247], v[96:111]
	s_waitcnt lgkmcnt(1)
	v_mfma_f32_32x32x16_bf16 v[80:95], v[228:231], v[240:243], v[80:95]
	s_waitcnt lgkmcnt(0)
	v_mfma_f32_32x32x16_bf16 v[64:79], v[228:231], v[244:247], v[64:79]
	s_waitcnt lgkmcnt(1)
	v_mfma_f32_32x32x16_bf16 v[48:63], v[232:235], v[240:243], v[48:63]
	s_waitcnt lgkmcnt(0)
	v_mfma_f32_32x32x16_bf16 v[32:47], v[232:235], v[244:247], v[32:47]
	s_waitcnt lgkmcnt(1)
	v_mfma_f32_32x32x16_bf16 v[16:31], v[236:239], v[240:243], v[16:31]
	s_waitcnt lgkmcnt(0)
	v_mfma_f32_32x32x16_bf16 v[0:15], v[236:239], v[244:247], v[0:15]
	s_waitcnt vmcnt(0)
	s_mul_i32 s41, s12, 0x1240
	s_add_u32 s46, s30, s41
	s_addc_u32 s47, s31, 0
	s_lshl_b32 s41, s8, 1
	s_add_u32 s46, s46, s41
	s_addc_u32 s47, s47, 0
	s_add_u32 s46, s46, 0x7157900
	s_addc_u32 s47, s47, 0
	s_cmp_eq_u32 s8, 0x900
	s_cselect_b32 s48, 2, 1
	v_cvt_pk_bf16_f32 v190, v112, v113
	v_cvt_pk_bf16_f32 v191, v114, v115
	v_cvt_pk_bf16_f32 v192, v116, v117
	v_cvt_pk_bf16_f32 v193, v118, v119
	v_cvt_pk_bf16_f32 v194, v120, v121
	v_cvt_pk_bf16_f32 v195, v122, v123
	v_cvt_pk_bf16_f32 v196, v124, v125
	v_cvt_pk_bf16_f32 v197, v126, v127
	v_cvt_pk_bf16_f32 v198, v96, v97
	v_cvt_pk_bf16_f32 v199, v98, v99
	v_cvt_pk_bf16_f32 v200, v100, v101
	v_cvt_pk_bf16_f32 v201, v102, v103
	v_cvt_pk_bf16_f32 v202, v104, v105
	v_cvt_pk_bf16_f32 v203, v106, v107
	v_cvt_pk_bf16_f32 v204, v108, v109
	v_cvt_pk_bf16_f32 v205, v110, v111
	v_cvt_pk_bf16_f32 v206, v80, v81
	v_cvt_pk_bf16_f32 v207, v82, v83
	v_cvt_pk_bf16_f32 v208, v84, v85
	v_cvt_pk_bf16_f32 v209, v86, v87
	v_cvt_pk_bf16_f32 v210, v88, v89
	v_cvt_pk_bf16_f32 v211, v90, v91
	v_cvt_pk_bf16_f32 v212, v92, v93
	v_cvt_pk_bf16_f32 v213, v94, v95
	v_cvt_pk_bf16_f32 v214, v64, v65
	v_cvt_pk_bf16_f32 v215, v66, v67
	v_cvt_pk_bf16_f32 v216, v68, v69
	v_cvt_pk_bf16_f32 v217, v70, v71
	v_cvt_pk_bf16_f32 v218, v72, v73
	v_cvt_pk_bf16_f32 v219, v74, v75
	v_cvt_pk_bf16_f32 v220, v76, v77
	v_cvt_pk_bf16_f32 v221, v78, v79
	v_cvt_pk_bf16_f32 v222, v48, v49
	v_cvt_pk_bf16_f32 v223, v50, v51
	v_cvt_pk_bf16_f32 v224, v52, v53
	v_cvt_pk_bf16_f32 v225, v54, v55
	v_cvt_pk_bf16_f32 v226, v56, v57
	v_cvt_pk_bf16_f32 v227, v58, v59
	v_cvt_pk_bf16_f32 v228, v60, v61
	v_cvt_pk_bf16_f32 v229, v62, v63
	v_cvt_pk_bf16_f32 v230, v32, v33
	v_cvt_pk_bf16_f32 v231, v34, v35
	v_cvt_pk_bf16_f32 v232, v36, v37
	v_cvt_pk_bf16_f32 v233, v38, v39
	v_cvt_pk_bf16_f32 v234, v40, v41
	v_cvt_pk_bf16_f32 v235, v42, v43
	v_cvt_pk_bf16_f32 v236, v44, v45
	v_cvt_pk_bf16_f32 v237, v46, v47
	v_cvt_pk_bf16_f32 v238, v16, v17
	v_cvt_pk_bf16_f32 v239, v18, v19
	v_cvt_pk_bf16_f32 v240, v20, v21
	v_cvt_pk_bf16_f32 v241, v22, v23
	v_cvt_pk_bf16_f32 v242, v24, v25
	v_cvt_pk_bf16_f32 v243, v26, v27
	v_cvt_pk_bf16_f32 v244, v28, v29
	v_cvt_pk_bf16_f32 v245, v30, v31
	v_cvt_pk_bf16_f32 v246, v0, v1
	v_cvt_pk_bf16_f32 v247, v2, v3
	v_cvt_pk_bf16_f32 v248, v4, v5
	v_cvt_pk_bf16_f32 v249, v6, v7
	v_cvt_pk_bf16_f32 v250, v8, v9
	v_cvt_pk_bf16_f32 v251, v10, v11
	v_cvt_pk_bf16_f32 v252, v12, v13
	v_cvt_pk_bf16_f32 v253, v14, v15
	s_branch .LBB0_1281
